# speedup vs baseline: 1.0034x; 1.0034x over previous
; #define RAW_BARRIER() do { asm volatile("s_waitcnt lgkmcnt(0)" ::: "memory"); __builtin_amdgcn_s_barrier(); } while (0)
; #define ISSUE_V(tt_, st_) do { \
;     const int kq_ = KEY0(tt_); char* vbuf_ = vbase + (st_) * VSZ; \
;     _Pragma("unroll") for (int i_ = 0; i_ < NV; ++i_) { const int j_ = wave8 * NV + i_, r_ = j_ * 8 + r8; \
;       __builtin_amdgcn_global_load_lds((const unsigned*)(VT + (size_t)r_ * KEYS + kq_ + ((p8 ^ ((r_ >> 1) & 7)) * 8)), (unsigned*)(vbuf_ + j_ * 1024 + lane * 16), 16, 0, 0); } \
;   } while (0)
; __device__ __forceinline__ int get_half() { return __builtin_amdgcn_readfirstlane((int)(threadIdx.x >> 8)); }
; template <int DKA, int DKB, int DV, bool BAND, bool SINK> ...
;     ...
;   for (int t = 0; t < ntT; ++t) {
;     const int k0 = KEY0(t);
;     const char* kst = sm + (t & 1) * KSZ;
;     const char* vbuf = vbase + (t & 1) * VSZ;
;     asm volatile("s_waitcnt vmcnt(0)" ::: "memory");
;     RAW_BARRIER();
;     if (t + 1 < ntT) { ISSUE_K(t + 1, (t + 1) & 1); ISSUE_V(t + 1, (t + 1) & 1); }
.LBB0_1542:
	v_readfirstlane_b32 s0, v206
	s_lshr_b32 s0, s0, 8
	s_cmp_eq_u32 s0, 0
	s_cbranch_scc1 .Lmla_noprio
	s_setprio 1
